# spatial-gating U stores in full-sector form (16 rows x 64 B per store) via an extra v_permlane16_swap stage
# baseline (speedup 1.0000x reference)
; DI float bf_lo(unsigned u) { return __uint_as_float(u << 16); }
; DI float bf_hi(unsigned u) { return __uint_as_float(u & 0xffff0000u); }
; DI void st_bf4(bf16_t* p, f32x4 v) { u32x2 w; w.x = pk2(v[0], v[1]); w.y = pk2(v[2], v[3]); *(u32x2*)p = w; }
; DI void sg_phase(const Params& p, lds_t* shm) {
;     ...
;       const int tok = w * 128 + ib * 32 + l31; const float bias = p.sg_b[g * 128 + ib * 32 + l31];
; #pragma unroll
;       for (int cc = 0; cc < 2; ++cc)
; #pragma unroll
;         for (int g4 = 0; g4 < 4; ++g4) {
;           bf16_t* up = U + (size_t)tok * DM + g * 128 + 32 * (2 * chalf + cc) + 8 * g4 + 4 * h;
;           const u32x2 uu = *(const u32x2*)up; f32x4 o;
;           o[0] = bf_lo(uu.x) * (acc[cc][4 * g4 + 0] + bias); o[1] = bf_hi(uu.x) * (acc[cc][4 * g4 + 1] + bias);
;           o[2] = bf_lo(uu.y) * (acc[cc][4 * g4 + 2] + bias); o[3] = bf_hi(uu.y) * (acc[cc][4 * g4 + 3] + bias);
;           st_bf4(up, o);
;         }
.Lsg_done:
	s_or_b64 exec, exec, s[6:7]
	s_lshl_b32 s8, s1, 1
	v_lshl_add_u64 v[68:69], v[66:67], 0, s[8:9]
	v_lshl_add_u64 v[68:69], v[68:69], 0, v[216:217]
	s_waitcnt vmcnt(8)
	s_nop 7
	s_nop 7
	v_pk_add_f32 v[16:17], v[16:17], v[194:195] op_sel_hi:[1,0]
	v_pk_add_f32 v[18:19], v[18:19], v[194:195] op_sel_hi:[1,0]
	v_pk_add_f32 v[20:21], v[20:21], v[194:195] op_sel_hi:[1,0]
	v_pk_add_f32 v[22:23], v[22:23], v[194:195] op_sel_hi:[1,0]
	v_pk_add_f32 v[24:25], v[24:25], v[194:195] op_sel_hi:[1,0]
	v_pk_add_f32 v[26:27], v[26:27], v[194:195] op_sel_hi:[1,0]
	v_pk_add_f32 v[28:29], v[28:29], v[194:195] op_sel_hi:[1,0]
	v_pk_add_f32 v[30:31], v[30:31], v[194:195] op_sel_hi:[1,0]
	v_pk_add_f32 v[0:1], v[0:1], v[194:195] op_sel_hi:[1,0]
	v_pk_add_f32 v[2:3], v[2:3], v[194:195] op_sel_hi:[1,0]
	v_pk_add_f32 v[4:5], v[4:5], v[194:195] op_sel_hi:[1,0]
	v_pk_add_f32 v[6:7], v[6:7], v[194:195] op_sel_hi:[1,0]
	v_pk_add_f32 v[8:9], v[8:9], v[194:195] op_sel_hi:[1,0]
	v_pk_add_f32 v[10:11], v[10:11], v[194:195] op_sel_hi:[1,0]
	v_pk_add_f32 v[12:13], v[12:13], v[194:195] op_sel_hi:[1,0]
	v_pk_add_f32 v[14:15], v[14:15], v[194:195] op_sel_hi:[1,0]
	s_nop 1
	v_permlane32_swap_b32_e32 v16, v20
	v_permlane32_swap_b32_e32 v17, v21
	v_permlane32_swap_b32_e32 v18, v22
	v_permlane32_swap_b32_e32 v19, v23
	v_permlane32_swap_b32_e32 v24, v28
	v_permlane32_swap_b32_e32 v25, v29
	v_permlane32_swap_b32_e32 v26, v30
	v_permlane32_swap_b32_e32 v27, v31
	v_permlane32_swap_b32_e32 v0, v4
	v_permlane32_swap_b32_e32 v1, v5
	v_permlane32_swap_b32_e32 v2, v6
	v_permlane32_swap_b32_e32 v3, v7
	v_permlane32_swap_b32_e32 v8, v12
	v_permlane32_swap_b32_e32 v9, v13
	v_permlane32_swap_b32_e32 v10, v14
	v_permlane32_swap_b32_e32 v11, v15
	v_mbcnt_lo_u32_b32 v224, -1, 0
	v_mbcnt_hi_u32_b32 v224, -1, v224
	v_bfe_u32 v218, v224, 4, 1
	v_sub_u32_e32 v219, 0, v218
	v_and_b32_e32 v218, 0xffff8020, v219
	v_lshl_add_u64 v[220:221], v[68:69], 0, v[218:219]
	s_mov_b32 s100, 0x8000
	s_mov_b32 s101, 0
	v_lshl_add_u64 v[222:223], v[220:221], 0, s[100:101]
	s_waitcnt vmcnt(7)
	v_lshlrev_b32_e32 v100, 16, v196
	v_and_b32_e32 v101, 0xffff0000, v196
	v_lshlrev_b32_e32 v102, 16, v197
	v_and_b32_e32 v103, 0xffff0000, v197
	v_lshlrev_b32_e32 v104, 16, v198
	v_and_b32_e32 v105, 0xffff0000, v198
	v_lshlrev_b32_e32 v106, 16, v199
	v_and_b32_e32 v107, 0xffff0000, v199
	v_pk_mul_f32 v[16:17], v[16:17], v[100:101]
	v_pk_mul_f32 v[18:19], v[18:19], v[102:103]
	v_pk_mul_f32 v[20:21], v[20:21], v[104:105]
	v_pk_mul_f32 v[22:23], v[22:23], v[106:107]
	v_cvt_pk_bf16_f32 v16, v16, v17
	v_cvt_pk_bf16_f32 v17, v18, v19
	v_cvt_pk_bf16_f32 v18, v20, v21
	v_cvt_pk_bf16_f32 v19, v22, v23
	s_waitcnt vmcnt(6)
	v_lshlrev_b32_e32 v108, 16, v200
	v_and_b32_e32 v109, 0xffff0000, v200
	v_lshlrev_b32_e32 v110, 16, v201
	v_and_b32_e32 v111, 0xffff0000, v201
	v_lshlrev_b32_e32 v112, 16, v202
	v_and_b32_e32 v113, 0xffff0000, v202
	v_lshlrev_b32_e32 v114, 16, v203
	v_and_b32_e32 v115, 0xffff0000, v203
	v_pk_mul_f32 v[24:25], v[24:25], v[108:109]
	v_pk_mul_f32 v[26:27], v[26:27], v[110:111]
	v_pk_mul_f32 v[28:29], v[28:29], v[112:113]
	v_pk_mul_f32 v[30:31], v[30:31], v[114:115]
	v_cvt_pk_bf16_f32 v24, v24, v25
	v_cvt_pk_bf16_f32 v25, v26, v27
	v_cvt_pk_bf16_f32 v26, v28, v29
	v_cvt_pk_bf16_f32 v27, v30, v31
	s_nop 1
	v_permlane16_swap_b32_e32 v16, v24
	v_permlane16_swap_b32_e32 v17, v25
	v_permlane16_swap_b32_e32 v18, v26
	v_permlane16_swap_b32_e32 v19, v27
	global_store_dwordx4 v[220:221], v[16:19], off
	global_store_dwordx4 v[222:223], v[24:27], off
	s_waitcnt vmcnt(5)
	v_lshlrev_b32_e32 v100, 16, v204
	v_and_b32_e32 v101, 0xffff0000, v204
	v_lshlrev_b32_e32 v102, 16, v205
	v_and_b32_e32 v103, 0xffff0000, v205
	v_lshlrev_b32_e32 v104, 16, v206
	v_and_b32_e32 v105, 0xffff0000, v206
	v_lshlrev_b32_e32 v106, 16, v207
	v_and_b32_e32 v107, 0xffff0000, v207
	v_pk_mul_f32 v[0:1], v[0:1], v[100:101]
	v_pk_mul_f32 v[2:3], v[2:3], v[102:103]
	v_pk_mul_f32 v[4:5], v[4:5], v[104:105]
	v_pk_mul_f32 v[6:7], v[6:7], v[106:107]
	v_cvt_pk_bf16_f32 v0, v0, v1
	v_cvt_pk_bf16_f32 v1, v2, v3
	v_cvt_pk_bf16_f32 v2, v4, v5
	v_cvt_pk_bf16_f32 v3, v6, v7
	s_waitcnt vmcnt(4)
	v_lshlrev_b32_e32 v108, 16, v208
	v_and_b32_e32 v109, 0xffff0000, v208
	v_lshlrev_b32_e32 v110, 16, v209
	v_and_b32_e32 v111, 0xffff0000, v209
	v_lshlrev_b32_e32 v112, 16, v210
	v_and_b32_e32 v113, 0xffff0000, v210
	v_lshlrev_b32_e32 v114, 16, v211
	v_and_b32_e32 v115, 0xffff0000, v211
	v_pk_mul_f32 v[8:9], v[8:9], v[108:109]
	v_pk_mul_f32 v[10:11], v[10:11], v[110:111]
	v_pk_mul_f32 v[12:13], v[12:13], v[112:113]
	v_pk_mul_f32 v[14:15], v[14:15], v[114:115]
	v_cvt_pk_bf16_f32 v8, v8, v9
	v_cvt_pk_bf16_f32 v9, v10, v11
	v_cvt_pk_bf16_f32 v10, v12, v13
	v_cvt_pk_bf16_f32 v11, v14, v15
	s_nop 1
	v_permlane16_swap_b32_e32 v0, v8
	v_permlane16_swap_b32_e32 v1, v9
	v_permlane16_swap_b32_e32 v2, v10
	v_permlane16_swap_b32_e32 v3, v11
	global_store_dwordx4 v[220:221], v[0:3], off offset:64
	global_store_dwordx4 v[222:223], v[8:11], off offset:64
	s_cmp_eq_u32 s0, 8
	s_cbranch_scc0 .LBB0_396
	s_add_i32 s3, s3, s90
	s_cmpk_gt_i32 s3, 0xff
	s_cbranch_scc0 .LBB0_387
